# GEMM: first K-iteration of every tile peeled with SrcC=0 on each accumulator's first MFMA; per-tile 128-VGPR accumulator zeroing removed
# baseline (speedup 1.0000x reference)
; #define PG8_STAGE(bufoff, gbase, voff) do { _Pragma("unroll") for (int _i = 0; _i < 2; ++_i) \
;         __builtin_amdgcn_global_load_lds((const unsigned*)((const char*)(gbase) + (voff)[_i]), (LAS unsigned*)(lds + (bufoff) + ldsw + _i * 8192), 16, 0, 0); } while (0)
; #define PG8_LDA(dst, b, h) do { _Pragma("unroll") for (int m = 0; m < 4; ++m) _Pragma("unroll") for (int k = 0; k < 2; ++k) dst[m][k] = *(const LAS bf16x8*)(lds + PG8_SA(b, h) + aoff + m * 2048 + k * 1024); } while (0)
; #define PG8_LDB(dst, b, h) do { _Pragma("unroll") for (int n = 0; n < 2; ++n) _Pragma("unroll") for (int k = 0; k < 2; ++k) dst[n][k] = *(const LAS bf16x8*)(lds + PG8_SB(b, h) + boff + n * 2048 + k * 1024); } while (0)
; #define PG8_WAIT_V(n) asm volatile("s_waitcnt vmcnt(" #n ")" ::: "memory")
; #define PG8_WAIT_L(n) asm volatile("s_waitcnt lgkmcnt(" #n ")" ::: "memory")
; #define PG8_BAR __builtin_amdgcn_s_barrier()
; #define PG8_SCHED __builtin_amdgcn_sched_barrier(0)
; template <class Epi>
; DI void gemm_phase(LAS unsigned char* lds, const Gemm g, const StaticOrder& S, const Epi& E, const int tid) {
;     ...
;     for (;;) {
;         const bool has_next = S.next(ui + 1, nxt);
;         const char* nA = has_next ? (const char*)g.A + (size_t)nxt.pm * tstep : cA; const char* nB = has_next ? (const char*)g.Bt + (size_t)nxt.pn * tstep : cB;
;         for (int t = 0; t < nt; t += 2) {
;             const bool last = (t == nt - 2);
;             const char* a1 = cA + (size_t)(t + 1) * kstep;
;             const char* a2 = last ? nA : cA + (size_t)(t + 2) * kstep; const char* b2 = last ? nB : cB + (size_t)(t + 2) * kstep;
;             const char* a3 = a2 + kstep; const char* b3 = b2 + kstep;
;             PG8_LDB(B0, 0, 0); PG8_SCHED; PG8_LDA(At, 0, 0); PG8_STAGE(PG8_SA(1, 1), a1 + hstep, voffA);
;             PG8_WAIT_L(8); PG8_BAR; PG8_WAIT_L(0); PG8_MMA(0, 0, At, B0); PG8_BAR; PG8_SCHED;
;             PG8_LDB(B1, 0, 1); PG8_STAGE(PG8_SB(0, 0), b2, voffB);
;             PG8_BAR; PG8_WAIT_L(0); PG8_MMA(0, 1, At, B1); PG8_BAR;
;             PG8_LDA(At, 0, 1); PG8_STAGE(PG8_SA(0, 0), a2, voffA);
;             PG8_BAR; PG8_WAIT_L(0); PG8_MMA(1, 0, At, B0); PG8_BAR; PG8_SCHED;
;             PG8_STAGE(PG8_SB(0, 1), b2 + hstep, voffB);
;             PG8_WAIT_V(6); PG8_BAR; PG8_MMA(1, 1, At, B1); PG8_BAR;
.LBB0_742:
	s_add_u32 s20, s20, 0x80
	s_addc_u32 s21, s21, 0
	s_add_u32 s81, s18, 0x100
	s_addc_u32 s82, s19, 0
	s_mov_b32 s18, 0
	ds_read_b128 v[138:141], v212
	ds_read_b128 v[150:153], v212 offset:1024
	ds_read_b128 v[154:157], v212 offset:2048
	ds_read_b128 v[158:161], v212 offset:3072
	s_add_i32 s83, s18, 2
	s_add_u32 s22, s20, 0x80
	s_addc_u32 s19, s21, 0
	s_cmp_eq_u32 s60, s18
	s_cselect_b32 s18, s8, s22
	s_cselect_b32 s19, s9, s19
	s_cselect_b32 s23, s17, s82
	s_cselect_b32 s22, s16, s81
	s_add_i32 m0, s49, 0xc000
	ds_read_b128 v[162:165], v148
	ds_read_b128 v[166:169], v148 offset:1024
	ds_read_b128 v[170:173], v148 offset:2048
	ds_read_b128 v[174:177], v148 offset:3072
	ds_read_b128 v[178:181], v148 offset:4096
	ds_read_b128 v[182:185], v148 offset:5120
	ds_read_b128 v[186:189], v148 offset:6144
	ds_read_b128 v[190:193], v148 offset:7168
	global_load_lds_dwordx4 v134, s[20:21]
	s_add_i32 m0, s49, 0xe000
	s_nop 0
	global_load_lds_dwordx4 v136, s[20:21]
	s_waitcnt lgkmcnt(8)
	s_barrier
	s_waitcnt lgkmcnt(0)
	s_setprio 1
	s_waitcnt lgkmcnt(0)
	v_mfma_f32_16x16x32_bf16 v[24:27], v[138:141], v[162:165], 0
	v_mfma_f32_16x16x32_bf16 v[28:31], v[154:157], v[162:165], 0
	v_mfma_f32_16x16x32_bf16 v[16:19], v[138:141], v[170:173], 0
	v_mfma_f32_16x16x32_bf16 v[20:23], v[154:157], v[170:173], 0
	v_mfma_f32_16x16x32_bf16 v[8:11], v[138:141], v[178:181], 0
	v_mfma_f32_16x16x32_bf16 v[12:15], v[154:157], v[178:181], 0
	v_mfma_f32_16x16x32_bf16 v[0:3], v[138:141], v[186:189], 0
	v_mfma_f32_16x16x32_bf16 v[4:7], v[154:157], v[186:189], 0
	v_mfma_f32_16x16x32_bf16 v[24:27], v[150:153], v[166:169], v[24:27]
	v_mfma_f32_16x16x32_bf16 v[28:31], v[158:161], v[166:169], v[28:31]
	v_mfma_f32_16x16x32_bf16 v[16:19], v[150:153], v[174:177], v[16:19]
	v_mfma_f32_16x16x32_bf16 v[20:23], v[158:161], v[174:177], v[20:23]
	v_mfma_f32_16x16x32_bf16 v[8:11], v[150:153], v[182:185], v[8:11]
	v_mfma_f32_16x16x32_bf16 v[12:15], v[158:161], v[182:185], v[12:15]
	v_mfma_f32_16x16x32_bf16 v[0:3], v[150:153], v[190:193], v[0:3]
	v_mfma_f32_16x16x32_bf16 v[4:7], v[158:161], v[190:193], v[4:7]
	s_setprio 0
	s_barrier
	s_add_i32 s89, 0, 0x14000
	s_add_i32 vcc_lo, s26, s4
	s_mov_b32 m0, vcc_lo
	ds_read_b128 v[194:197], v213
	ds_read_b128 v[200:203], v213 offset:1024
	ds_read_b128 v[204:207], v213 offset:2048
	ds_read_b128 v[208:211], v213 offset:3072
	global_load_lds_dwordx4 v198, s[22:23]
	s_add_i32 m0, vcc_lo, 0x2000
	s_nop 0
	global_load_lds_dwordx4 v128, s[22:23]
	s_barrier
	s_waitcnt lgkmcnt(0)
	s_setprio 1
	s_waitcnt lgkmcnt(0)
	v_mfma_f32_16x16x32_bf16 v[88:91], v[194:197], v[162:165], 0
	v_mfma_f32_16x16x32_bf16 v[96:99], v[204:207], v[162:165], 0
	v_mfma_f32_16x16x32_bf16 v[80:83], v[194:197], v[170:173], 0
	v_mfma_f32_16x16x32_bf16 v[84:87], v[204:207], v[170:173], 0
	v_mfma_f32_16x16x32_bf16 v[72:75], v[194:197], v[178:181], 0
	v_mfma_f32_16x16x32_bf16 v[76:79], v[204:207], v[178:181], 0
	v_mfma_f32_16x16x32_bf16 v[56:59], v[194:197], v[186:189], 0
	v_mfma_f32_16x16x32_bf16 v[64:67], v[204:207], v[186:189], 0
	v_mfma_f32_16x16x32_bf16 v[88:91], v[200:203], v[166:169], v[88:91]
	v_mfma_f32_16x16x32_bf16 v[96:99], v[208:211], v[166:169], v[96:99]
	v_mfma_f32_16x16x32_bf16 v[80:83], v[200:203], v[174:177], v[80:83]
	v_mfma_f32_16x16x32_bf16 v[84:87], v[208:211], v[174:177], v[84:87]
	v_mfma_f32_16x16x32_bf16 v[72:75], v[200:203], v[182:185], v[72:75]
	v_mfma_f32_16x16x32_bf16 v[76:79], v[208:211], v[182:185], v[76:79]
	v_mfma_f32_16x16x32_bf16 v[56:59], v[200:203], v[190:193], v[56:59]
	v_mfma_f32_16x16x32_bf16 v[64:67], v[208:211], v[190:193], v[64:67]
	s_setprio 0
	s_mov_b32 m0, s49
	s_barrier
	ds_read_b128 v[162:165], v148 offset:16384
	ds_read_b128 v[166:169], v148 offset:17408
	ds_read_b128 v[170:173], v148 offset:18432
	ds_read_b128 v[174:177], v148 offset:19456
	ds_read_b128 v[178:181], v148 offset:20480
	ds_read_b128 v[182:185], v148 offset:21504
	ds_read_b128 v[186:189], v148 offset:22528
	ds_read_b128 v[190:193], v148 offset:23552
	global_load_lds_dwordx4 v132, s[18:19]
	s_mov_b32 m0, s52
	s_nop 0
	global_load_lds_dwordx4 v130, s[18:19]
	s_barrier
	s_waitcnt lgkmcnt(0)
	s_setprio 1
	s_waitcnt lgkmcnt(0)
	v_mfma_f32_16x16x32_bf16 v[60:63], v[138:141], v[162:165], 0
	v_mfma_f32_16x16x32_bf16 v[68:71], v[154:157], v[162:165], 0
	v_mfma_f32_16x16x32_bf16 v[48:51], v[138:141], v[170:173], 0
	v_mfma_f32_16x16x32_bf16 v[52:55], v[154:157], v[170:173], 0
	v_mfma_f32_16x16x32_bf16 v[40:43], v[138:141], v[178:181], 0
	v_mfma_f32_16x16x32_bf16 v[44:47], v[154:157], v[178:181], 0
	v_mfma_f32_16x16x32_bf16 v[32:35], v[138:141], v[186:189], 0
	v_mfma_f32_16x16x32_bf16 v[36:39], v[154:157], v[186:189], 0
	v_mfma_f32_16x16x32_bf16 v[60:63], v[150:153], v[166:169], v[60:63]
	v_mfma_f32_16x16x32_bf16 v[68:71], v[158:161], v[166:169], v[68:71]
	v_mfma_f32_16x16x32_bf16 v[48:51], v[150:153], v[174:177], v[48:51]
	v_mfma_f32_16x16x32_bf16 v[52:55], v[158:161], v[174:177], v[52:55]
	v_mfma_f32_16x16x32_bf16 v[40:43], v[150:153], v[182:185], v[40:43]
	v_mfma_f32_16x16x32_bf16 v[44:47], v[158:161], v[182:185], v[44:47]
	v_mfma_f32_16x16x32_bf16 v[32:35], v[150:153], v[190:193], v[32:35]
	v_mfma_f32_16x16x32_bf16 v[36:39], v[158:161], v[190:193], v[36:39]
	s_setprio 0
	s_barrier
	s_add_u32 s22, s22, s84
	s_addc_u32 s23, s23, 0
	s_add_i32 s89, s89, s4
	s_mov_b32 m0, s89
	s_nop 0
	global_load_lds_dwordx4 v198, s[22:23]
	s_add_i32 m0, s89, 0x2000
	s_nop 0
	global_load_lds_dwordx4 v128, s[22:23]
	s_waitcnt vmcnt(6)
	s_barrier
; #define PG8_STAGE(bufoff, gbase, voff) do { _Pragma("unroll") for (int _i = 0; _i < 2; ++_i) \
;         __builtin_amdgcn_global_load_lds((const unsigned*)((const char*)(gbase) + (voff)[_i]), (LAS unsigned*)(lds + (bufoff) + ldsw + _i * 8192), 16, 0, 0); } while (0)
; #define PG8_LDA(dst, b, h) do { _Pragma("unroll") for (int m = 0; m < 4; ++m) _Pragma("unroll") for (int k = 0; k < 2; ++k) dst[m][k] = *(const LAS bf16x8*)(lds + PG8_SA(b, h) + aoff + m * 2048 + k * 1024); } while (0)
; #define PG8_LDB(dst, b, h) do { _Pragma("unroll") for (int n = 0; n < 2; ++n) _Pragma("unroll") for (int k = 0; k < 2; ++k) dst[n][k] = *(const LAS bf16x8*)(lds + PG8_SB(b, h) + boff + n * 2048 + k * 1024); } while (0)
; #define PG8_MMA(ai, bj, At, Bt) do { __builtin_amdgcn_s_setprio(1); _Pragma("unroll") for (int m = 0; m < 4; ++m) _Pragma("unroll") for (int n = 0; n < 2; ++n) _Pragma("unroll") for (int k = 0; k < 2; ++k) \
;         acc[ai][bj][m][n] = __builtin_amdgcn_mfma_f32_16x16x32_bf16(Bt[n][k], At[m][k], acc[ai][bj][m][n], 0, 0, 0); __builtin_amdgcn_s_setprio(0); } while (0)
; #define PG8_WAIT_V(n) asm volatile("s_waitcnt vmcnt(" #n ")" ::: "memory")
; #define PG8_WAIT_L(n) asm volatile("s_waitcnt lgkmcnt(" #n ")" ::: "memory")
; #define PG8_BAR __builtin_amdgcn_s_barrier()
; #define PG8_SCHED __builtin_amdgcn_sched_barrier(0)
; template <class Epi>
; DI void gemm_phase(LAS unsigned char* lds, const Gemm g, const StaticOrder& S, const Epi& E, const int tid) {
;     ...
;             PG8_WAIT_V(6); PG8_BAR; PG8_MMA(1, 1, At, B1); PG8_BAR;
;             PG8_LDB(B0, 1, 0); PG8_SCHED; PG8_LDA(At, 1, 0); PG8_STAGE(PG8_SA(0, 1), a2 + hstep, voffA);
;             PG8_WAIT_L(8); PG8_BAR; PG8_WAIT_L(0); PG8_MMA(0, 0, At, B0); PG8_BAR; PG8_SCHED;
;             PG8_LDB(B1, 1, 1); PG8_STAGE(PG8_SB(1, 0), b3, voffB);
;             PG8_BAR; PG8_WAIT_L(0); PG8_MMA(0, 1, At, B1); PG8_BAR;
;             PG8_LDA(At, 1, 1); PG8_STAGE(PG8_SA(1, 0), a3, voffA);
;             PG8_BAR; PG8_WAIT_L(0); PG8_MMA(1, 0, At, B0); PG8_BAR; PG8_SCHED;
;             PG8_STAGE(PG8_SB(1, 1), b3 + hstep, voffB);
;             PG8_WAIT_V(6); PG8_BAR; PG8_MMA(1, 1, At, B1); PG8_BAR;
	s_setprio 1
	v_mfma_f32_16x16x32_bf16 v[120:123], v[194:197], v[162:165], 0
	v_mfma_f32_16x16x32_bf16 v[124:127], v[204:207], v[162:165], 0
	v_mfma_f32_16x16x32_bf16 v[112:115], v[194:197], v[170:173], 0
	v_mfma_f32_16x16x32_bf16 v[116:119], v[204:207], v[170:173], 0
	v_mfma_f32_16x16x32_bf16 v[104:107], v[194:197], v[178:181], 0
	v_mfma_f32_16x16x32_bf16 v[108:111], v[204:207], v[178:181], 0
	v_mfma_f32_16x16x32_bf16 v[92:95], v[194:197], v[186:189], 0
	v_mfma_f32_16x16x32_bf16 v[100:103], v[204:207], v[186:189], 0
	v_mfma_f32_16x16x32_bf16 v[120:123], v[200:203], v[166:169], v[120:123]
	v_mfma_f32_16x16x32_bf16 v[124:127], v[208:211], v[166:169], v[124:127]
	v_mfma_f32_16x16x32_bf16 v[112:115], v[200:203], v[174:177], v[112:115]
	v_mfma_f32_16x16x32_bf16 v[116:119], v[208:211], v[174:177], v[116:119]
	v_mfma_f32_16x16x32_bf16 v[104:107], v[200:203], v[182:185], v[104:107]
	v_mfma_f32_16x16x32_bf16 v[108:111], v[208:211], v[182:185], v[108:111]
	v_mfma_f32_16x16x32_bf16 v[92:95], v[200:203], v[190:193], v[92:95]
	v_mfma_f32_16x16x32_bf16 v[100:103], v[208:211], v[190:193], v[100:103]
	s_setprio 0
	s_add_i32 s22, 0, 0x18000
	s_barrier
	ds_read_b128 v[138:141], v214
	ds_read_b128 v[150:153], v214 offset:1024
	ds_read_b128 v[154:157], v214 offset:2048
	ds_read_b128 v[158:161], v214 offset:3072
	s_add_u32 s18, s18, s84
	s_addc_u32 s19, s19, 0
	s_mov_b32 m0, s53
	ds_read_b128 v[162:165], v148 offset:32768
	ds_read_b128 v[166:169], v148 offset:33792
	ds_read_b128 v[170:173], v148 offset:34816
	ds_read_b128 v[174:177], v148 offset:35840
	ds_read_b128 v[178:181], v148 offset:36864
	ds_read_b128 v[182:185], v148 offset:37888
	ds_read_b128 v[186:189], v148 offset:38912
	ds_read_b128 v[190:193], v148 offset:39936
	global_load_lds_dwordx4 v132, s[18:19]
	s_mov_b32 m0, s54
	s_nop 0
	global_load_lds_dwordx4 v130, s[18:19]
	s_waitcnt lgkmcnt(8)
	s_barrier
	s_waitcnt lgkmcnt(0)
	s_setprio 1
	s_waitcnt lgkmcnt(0)
	v_mfma_f32_16x16x32_bf16 v[24:27], v[138:141], v[162:165], v[24:27]
	v_mfma_f32_16x16x32_bf16 v[28:31], v[154:157], v[162:165], v[28:31]
	v_mfma_f32_16x16x32_bf16 v[16:19], v[138:141], v[170:173], v[16:19]
	v_mfma_f32_16x16x32_bf16 v[20:23], v[154:157], v[170:173], v[20:23]
	v_mfma_f32_16x16x32_bf16 v[8:11], v[138:141], v[178:181], v[8:11]
	v_mfma_f32_16x16x32_bf16 v[12:15], v[154:157], v[178:181], v[12:15]
	v_mfma_f32_16x16x32_bf16 v[0:3], v[138:141], v[186:189], v[0:3]
	v_mfma_f32_16x16x32_bf16 v[4:7], v[154:157], v[186:189], v[4:7]
	v_mfma_f32_16x16x32_bf16 v[24:27], v[150:153], v[166:169], v[24:27]
	v_mfma_f32_16x16x32_bf16 v[28:31], v[158:161], v[166:169], v[28:31]
	v_mfma_f32_16x16x32_bf16 v[16:19], v[150:153], v[174:177], v[16:19]
	v_mfma_f32_16x16x32_bf16 v[20:23], v[158:161], v[174:177], v[20:23]
	v_mfma_f32_16x16x32_bf16 v[8:11], v[150:153], v[182:185], v[8:11]
	v_mfma_f32_16x16x32_bf16 v[12:15], v[158:161], v[182:185], v[12:15]
	v_mfma_f32_16x16x32_bf16 v[0:3], v[150:153], v[190:193], v[0:3]
	v_mfma_f32_16x16x32_bf16 v[4:7], v[158:161], v[190:193], v[4:7]
	s_setprio 0
	s_barrier
	s_add_i32 s18, 0, 0x1c000
	s_add_i32 s19, s22, s4
	s_mov_b32 m0, s19
	ds_read_b128 v[194:197], v215
	ds_read_b128 v[200:203], v215 offset:1024
	ds_read_b128 v[204:207], v215 offset:2048
	ds_read_b128 v[208:211], v215 offset:3072
	s_add_i32 vcc_hi, s60, 2
	s_cmp_eq_u32 vcc_hi, s83
	s_cselect_b32 s100, s16, s81
	s_cselect_b32 s101, s17, s82
	s_add_u32 s100, s100, 0x80
	s_addc_u32 s101, s101, 0
	global_load_lds_dwordx4 v198, s[100:101]
	s_add_i32 m0, s19, 0x2000
	s_nop 0
	global_load_lds_dwordx4 v128, s[100:101]
	s_barrier
	s_waitcnt lgkmcnt(0)
	s_setprio 1
	s_waitcnt lgkmcnt(0)
	v_mfma_f32_16x16x32_bf16 v[88:91], v[194:197], v[162:165], v[88:91]
	v_mfma_f32_16x16x32_bf16 v[96:99], v[204:207], v[162:165], v[96:99]
	v_mfma_f32_16x16x32_bf16 v[80:83], v[194:197], v[170:173], v[80:83]
	v_mfma_f32_16x16x32_bf16 v[84:87], v[204:207], v[170:173], v[84:87]
	v_mfma_f32_16x16x32_bf16 v[72:75], v[194:197], v[178:181], v[72:75]
	v_mfma_f32_16x16x32_bf16 v[76:79], v[204:207], v[178:181], v[76:79]
	v_mfma_f32_16x16x32_bf16 v[56:59], v[194:197], v[186:189], v[56:59]
	v_mfma_f32_16x16x32_bf16 v[64:67], v[204:207], v[186:189], v[64:67]
	v_mfma_f32_16x16x32_bf16 v[88:91], v[200:203], v[166:169], v[88:91]
	v_mfma_f32_16x16x32_bf16 v[96:99], v[208:211], v[166:169], v[96:99]
	v_mfma_f32_16x16x32_bf16 v[80:83], v[200:203], v[174:177], v[80:83]
	v_mfma_f32_16x16x32_bf16 v[84:87], v[208:211], v[174:177], v[84:87]
	v_mfma_f32_16x16x32_bf16 v[72:75], v[200:203], v[182:185], v[72:75]
	v_mfma_f32_16x16x32_bf16 v[76:79], v[208:211], v[182:185], v[76:79]
	v_mfma_f32_16x16x32_bf16 v[56:59], v[200:203], v[190:193], v[56:59]
	v_mfma_f32_16x16x32_bf16 v[64:67], v[208:211], v[190:193], v[64:67]
	s_setprio 0
	s_mov_b32 m0, s55
	s_barrier
; #define PG8_STAGE(bufoff, gbase, voff) do { _Pragma("unroll") for (int _i = 0; _i < 2; ++_i) \
;         __builtin_amdgcn_global_load_lds((const unsigned*)((const char*)(gbase) + (voff)[_i]), (LAS unsigned*)(lds + (bufoff) + ldsw + _i * 8192), 16, 0, 0); } while (0)
; #define PG8_LDA(dst, b, h) do { _Pragma("unroll") for (int m = 0; m < 4; ++m) _Pragma("unroll") for (int k = 0; k < 2; ++k) dst[m][k] = *(const LAS bf16x8*)(lds + PG8_SA(b, h) + aoff + m * 2048 + k * 1024); } while (0)
; #define PG8_MMA(ai, bj, At, Bt) do { __builtin_amdgcn_s_setprio(1); _Pragma("unroll") for (int m = 0; m < 4; ++m) _Pragma("unroll") for (int n = 0; n < 2; ++n) _Pragma("unroll") for (int k = 0; k < 2; ++k) \
;         acc[ai][bj][m][n] = __builtin_amdgcn_mfma_f32_16x16x32_bf16(Bt[n][k], At[m][k], acc[ai][bj][m][n], 0, 0, 0); __builtin_amdgcn_s_setprio(0); } while (0)
; #define PG8_WAIT_V(n) asm volatile("s_waitcnt vmcnt(" #n ")" ::: "memory")
; #define PG8_WAIT_L(n) asm volatile("s_waitcnt lgkmcnt(" #n ")" ::: "memory")
; #define PG8_BAR __builtin_amdgcn_s_barrier()
; #define PG8_SCHED __builtin_amdgcn_sched_barrier(0)
; template <class Epi>
; DI void gemm_phase(LAS unsigned char* lds, const Gemm g, const StaticOrder& S, const Epi& E, const int tid) {
;     ...
;             PG8_LDA(At, 1, 1); PG8_STAGE(PG8_SA(1, 0), a3, voffA);
;             PG8_BAR; PG8_WAIT_L(0); PG8_MMA(1, 0, At, B0); PG8_BAR; PG8_SCHED;
;             PG8_STAGE(PG8_SB(1, 1), b3 + hstep, voffB);
;             PG8_WAIT_V(6); PG8_BAR; PG8_MMA(1, 1, At, B1); PG8_BAR;
;         }
;         E(acc, cur, wr, wc, fr, fq);
;         if (!has_next) break;
	ds_read_b128 v[162:165], v148 offset:49152
	ds_read_b128 v[166:169], v148 offset:50176
	ds_read_b128 v[170:173], v148 offset:51200
	ds_read_b128 v[174:177], v148 offset:52224
	ds_read_b128 v[178:181], v148 offset:53248
	ds_read_b128 v[182:185], v148 offset:54272
	ds_read_b128 v[186:189], v148 offset:55296
	ds_read_b128 v[190:193], v148 offset:56320
	s_add_u32 s100, s20, 0x80
	s_addc_u32 s101, s21, 0
	s_add_i32 vcc_hi, s60, 2
	s_cmp_eq_u32 vcc_hi, s83
	s_cselect_b32 s100, s8, s100
	s_cselect_b32 s101, s9, s101
	s_add_u32 s100, s100, 0x80
	s_addc_u32 s101, s101, 0
	global_load_lds_dwordx4 v132, s[100:101]
	s_mov_b32 m0, s56
	s_nop 0
	global_load_lds_dwordx4 v130, s[100:101]
	s_barrier
	s_waitcnt lgkmcnt(0)
	s_setprio 1
	s_waitcnt lgkmcnt(0)
	v_mfma_f32_16x16x32_bf16 v[60:63], v[138:141], v[162:165], v[60:63]
	v_mfma_f32_16x16x32_bf16 v[68:71], v[154:157], v[162:165], v[68:71]
	v_mfma_f32_16x16x32_bf16 v[48:51], v[138:141], v[170:173], v[48:51]
	v_mfma_f32_16x16x32_bf16 v[52:55], v[154:157], v[170:173], v[52:55]
	v_mfma_f32_16x16x32_bf16 v[40:43], v[138:141], v[178:181], v[40:43]
	v_mfma_f32_16x16x32_bf16 v[44:47], v[154:157], v[178:181], v[44:47]
	v_mfma_f32_16x16x32_bf16 v[32:35], v[138:141], v[186:189], v[32:35]
	v_mfma_f32_16x16x32_bf16 v[36:39], v[154:157], v[186:189], v[36:39]
	v_mfma_f32_16x16x32_bf16 v[60:63], v[150:153], v[166:169], v[60:63]
	v_mfma_f32_16x16x32_bf16 v[68:71], v[158:161], v[166:169], v[68:71]
	v_mfma_f32_16x16x32_bf16 v[48:51], v[150:153], v[174:177], v[48:51]
	v_mfma_f32_16x16x32_bf16 v[52:55], v[158:161], v[174:177], v[52:55]
	v_mfma_f32_16x16x32_bf16 v[40:43], v[150:153], v[182:185], v[40:43]
	v_mfma_f32_16x16x32_bf16 v[44:47], v[158:161], v[182:185], v[44:47]
	v_mfma_f32_16x16x32_bf16 v[32:35], v[150:153], v[190:193], v[32:35]
	v_mfma_f32_16x16x32_bf16 v[36:39], v[158:161], v[190:193], v[36:39]
	s_setprio 0
	s_barrier
	s_add_i32 s18, s18, s4
	s_add_i32 vcc_hi, s60, 2
	s_cmp_eq_u32 vcc_hi, s83
	s_cselect_b32 s100, s16, s81
	s_cselect_b32 s101, s17, s82
	s_add_u32 s100, s100, s84
	s_addc_u32 s101, s101, 0
	s_add_u32 s100, s100, 0x80
	s_addc_u32 s101, s101, 0
	s_mov_b32 m0, s18
	s_nop 0
	global_load_lds_dwordx4 v198, s[100:101]
	s_add_i32 m0, s18, 0x2000
	s_nop 0
	global_load_lds_dwordx4 v128, s[100:101]
	s_waitcnt vmcnt(6)
	s_barrier
	s_setprio 1
	v_mfma_f32_16x16x32_bf16 v[120:123], v[194:197], v[162:165], v[120:123]
	v_mfma_f32_16x16x32_bf16 v[124:127], v[204:207], v[162:165], v[124:127]
	v_mfma_f32_16x16x32_bf16 v[112:115], v[194:197], v[170:173], v[112:115]
	v_mfma_f32_16x16x32_bf16 v[116:119], v[204:207], v[170:173], v[116:119]
	v_mfma_f32_16x16x32_bf16 v[104:107], v[194:197], v[178:181], v[104:107]
	v_mfma_f32_16x16x32_bf16 v[108:111], v[204:207], v[178:181], v[108:111]
	v_mfma_f32_16x16x32_bf16 v[92:95], v[194:197], v[186:189], v[92:95]
	v_mfma_f32_16x16x32_bf16 v[100:103], v[204:207], v[186:189], v[100:103]
	v_mfma_f32_16x16x32_bf16 v[120:123], v[200:203], v[166:169], v[120:123]
	v_mfma_f32_16x16x32_bf16 v[124:127], v[208:211], v[166:169], v[124:127]
	v_mfma_f32_16x16x32_bf16 v[112:115], v[200:203], v[174:177], v[112:115]
	v_mfma_f32_16x16x32_bf16 v[116:119], v[208:211], v[174:177], v[116:119]
	v_mfma_f32_16x16x32_bf16 v[104:107], v[200:203], v[182:185], v[104:107]
	v_mfma_f32_16x16x32_bf16 v[108:111], v[208:211], v[182:185], v[108:111]
	v_mfma_f32_16x16x32_bf16 v[92:95], v[200:203], v[190:193], v[92:95]
	v_mfma_f32_16x16x32_bf16 v[100:103], v[208:211], v[190:193], v[100:103]
	s_setprio 0
	s_add_u32 s20, s20, 0x100
	s_addc_u32 s21, s21, 0
	s_add_u32 s81, s81, 0x100
	s_addc_u32 s82, s82, 0
	s_cmp_ge_u32 s83, s57
	s_mov_b32 s18, s83
	s_barrier
	s_cbranch_scc0 .LBB0_743
	s_branch .Lgemm_epi

; DI unsigned pk2(float lo, float hi) { f32x2 v = {lo, hi}; bf16v2 b = __builtin_convertvector(v, bf16v2); return __builtin_bit_cast(unsigned, b); }
; DI float silu_f(float x) { return x * __builtin_amdgcn_rcpf(1.f + __expf(-x)); }
;     DI void operator()(const f32x4 (&acc)[2][2][4][2], const Unit& u, int wr, int wc, int fr, int fq) const {
;         const int row0 = u.pm * BM + wr * 64 + fr, col0 = u.pn * HALF + wc * 32 + 8 * fq;
; #pragma unroll
;         for (int ai = 0; ai < 2; ++ai)
; #pragma unroll
;             for (int m = 0; m < 4; ++m) { bf16_t* rowp = O + (size_t)(row0 + ai * HALF + m * 16) * ldc + col0;
;                 float r[8];
; #pragma unroll
;                 for (int n = 0; n < 2; ++n)
; #pragma unroll
;                     for (int e = 0; e < 4; ++e) { const float g = acc[ai][0][m][n][e], up = acc[ai][1][m][n][e]; r[n * 4 + e] = silu_f(g) * up; }
;                 u32x4 o; o.x = pk2(r[0], r[1]); o.y = pk2(r[2], r[3]); o.z = pk2(r[4], r[5]); o.w = pk2(r[6], r[7]);
;                 *(u32x4*)rowp = o; }
.Lgemm_epi:
	v_lshl_add_u32 v140, s80, 8, v145
	v_ashrrev_i32_e32 v138, 31, v140
	v_mul_lo_u32 v157, s78, v138
	v_mul_lo_u32 v141, s79, v140
	v_mad_u64_u32 v[138:139], s[18:19], s78, v140, 0
	v_or_b32_e32 v162, 16, v140
	v_or_b32_e32 v160, 32, v140
	v_or_b32_e32 v158, 48, v140
	v_add_u32_e32 v154, 0x80, v140
	v_add_u32_e32 v151, 0x90, v140
	v_add3_u32 v139, v139, v157, v141
	s_mov_b64 s[18:19], -1
	s_andn2_b64 vcc, exec, s[14:15]
	v_mul_lo_u32 v163, s79, v162
	v_mul_lo_u32 v161, s79, v160
	v_mul_lo_u32 v159, s79, v158
	v_ashrrev_i32_e32 v156, 31, v154
	v_mul_lo_u32 v155, s79, v154
	v_ashrrev_i32_e32 v153, 31, v151
	v_mul_lo_u32 v152, s79, v151
	v_add_u32_e32 v150, 0xa0, v140
	v_add_u32_e32 v149, 0xb0, v140
	s_cbranch_vccnz .LBB0_746
	v_mul_f32_e32 v140, 0xbfb8aa3b, v24
	v_mul_f32_e32 v141, 0xbfb8aa3b, v25
	v_mul_f32_e32 v166, 0xbfb8aa3b, v26
	v_mul_f32_e32 v167, 0xbfb8aa3b, v27
	v_mul_f32_e32 v168, 0xbfb8aa3b, v28
	v_mul_f32_e32 v169, 0xbfb8aa3b, v29
	v_exp_f32_e32 v140, v140
	v_exp_f32_e32 v141, v141
	v_exp_f32_e32 v166, v166
	v_exp_f32_e32 v167, v167
	v_exp_f32_e32 v168, v168
	v_exp_f32_e32 v169, v169
	v_mul_f32_e32 v170, 0xbfb8aa3b, v30
	v_mul_f32_e32 v171, 0xbfb8aa3b, v31
	v_add_f32_e32 v140, 1.0, v140
	v_add_f32_e32 v141, 1.0, v141
	v_add_f32_e32 v166, 1.0, v166
	v_add_f32_e32 v167, 1.0, v167
	v_add_f32_e32 v168, 1.0, v168
	v_add_f32_e32 v169, 1.0, v169
	v_exp_f32_e32 v170, v170
	v_exp_f32_e32 v171, v171
	v_rcp_f32_e32 v164, v140
	v_rcp_f32_e32 v165, v141
	v_rcp_f32_e32 v166, v166
	v_rcp_f32_e32 v167, v167
	v_rcp_f32_e32 v168, v168
	v_rcp_f32_e32 v169, v169
	v_add_f32_e32 v170, 1.0, v170
	v_add_f32_e32 v171, 1.0, v171
	v_pk_mul_f32 v[164:165], v[24:25], v[164:165]
	v_pk_mul_f32 v[166:167], v[26:27], v[166:167]
	v_rcp_f32_e32 v170, v170
	v_rcp_f32_e32 v171, v171
	v_pk_mul_f32 v[168:169], v[28:29], v[168:169]
	v_pk_mul_f32 v[164:165], v[164:165], v[88:89]
	v_pk_mul_f32 v[166:167], v[166:167], v[90:91]
	v_pk_mul_f32 v[168:169], v[168:169], v[96:97]
	v_cvt_pk_bf16_f32 v164, v164, v165
	v_cvt_pk_bf16_f32 v165, v166, v167
	v_cvt_pk_bf16_f32 v166, v168, v169
	v_mul_f32_e32 v168, 0xbfb8aa3b, v16
	v_mul_f32_e32 v169, 0xbfb8aa3b, v17
	v_lshl_or_b32 v140, s77, 7, v147
	v_readlane_b32 s18, v255, 30
	v_exp_f32_e32 v168, v168
	v_exp_f32_e32 v169, v169
	v_ashrrev_i32_e32 v141, 31, v140
	v_readlane_b32 s19, v255, 31
	v_pk_mul_f32 v[170:171], v[30:31], v[170:171]
	s_nop 0
	v_lshl_add_u64 v[140:141], v[140:141], 1, s[18:19]
	v_pk_mul_f32 v[170:171], v[170:171], v[98:99]
	v_lshl_add_u64 v[172:173], v[138:139], 1, v[140:141]
	v_cvt_pk_bf16_f32 v167, v170, v171
	global_store_dwordx4 v[172:173], v[164:167], off
	v_mul_f32_e32 v170, 0xbfb8aa3b, v20
	v_mul_f32_e32 v171, 0xbfb8aa3b, v21
	v_add_f32_e32 v164, 1.0, v168
	v_add_f32_e32 v165, 1.0, v169
	v_mul_f32_e32 v168, 0xbfb8aa3b, v18
	v_mul_f32_e32 v169, 0xbfb8aa3b, v19
	v_exp_f32_e32 v168, v168
	v_exp_f32_e32 v169, v169
	v_mul_f32_e32 v172, 0xbfb8aa3b, v22
	v_mul_f32_e32 v173, 0xbfb8aa3b, v23
	v_add_f32_e32 v168, 1.0, v168
	v_add_f32_e32 v169, 1.0, v169
	v_exp_f32_e32 v170, v170
	v_exp_f32_e32 v171, v171
	v_exp_f32_e32 v172, v172
	v_exp_f32_e32 v173, v173
	v_rcp_f32_e32 v164, v164
	v_rcp_f32_e32 v165, v165
	v_rcp_f32_e32 v168, v168
	v_rcp_f32_e32 v169, v169
	v_add_f32_e32 v170, 1.0, v170
	v_add_f32_e32 v171, 1.0, v171
	v_add_f32_e32 v172, 1.0, v172
	v_add_f32_e32 v173, 1.0, v173
	v_pk_mul_f32 v[164:165], v[16:17], v[164:165]
	v_pk_mul_f32 v[168:169], v[18:19], v[168:169]
	v_rcp_f32_e32 v170, v170
	v_rcp_f32_e32 v171, v171
	v_rcp_f32_e32 v172, v172
	v_rcp_f32_e32 v173, v173
	v_pk_mul_f32 v[164:165], v[164:165], v[80:81]
	v_pk_mul_f32 v[168:169], v[168:169], v[82:83]
	v_cvt_pk_bf16_f32 v164, v164, v165
	v_cvt_pk_bf16_f32 v165, v168, v169
	v_mul_f32_e32 v168, 0xbfb8aa3b, v8
	v_mul_f32_e32 v169, 0xbfb8aa3b, v9
	v_exp_f32_e32 v168, v168
	v_exp_f32_e32 v169, v169
	v_mad_u64_u32 v[166:167], s[18:19], s78, v162, 0
	v_pk_mul_f32 v[170:171], v[20:21], v[170:171]
	v_pk_mul_f32 v[172:173], v[22:23], v[172:173]
	v_add3_u32 v167, v167, v157, v163
	v_pk_mul_f32 v[170:171], v[170:171], v[84:85]
	v_pk_mul_f32 v[172:173], v[172:173], v[86:87]
	v_lshl_add_u64 v[174:175], v[166:167], 1, v[140:141]
	v_cvt_pk_bf16_f32 v166, v170, v171
	v_cvt_pk_bf16_f32 v167, v172, v173
	global_store_dwordx4 v[174:175], v[164:167], off
	v_mul_f32_e32 v170, 0xbfb8aa3b, v12
	v_mul_f32_e32 v171, 0xbfb8aa3b, v13
	v_add_f32_e32 v164, 1.0, v168
	v_add_f32_e32 v165, 1.0, v169
	v_mul_f32_e32 v168, 0xbfb8aa3b, v10
	v_mul_f32_e32 v169, 0xbfb8aa3b, v11
	v_exp_f32_e32 v168, v168
	v_exp_f32_e32 v169, v169
	v_mul_f32_e32 v172, 0xbfb8aa3b, v14
	v_mul_f32_e32 v173, 0xbfb8aa3b, v15
	v_add_f32_e32 v168, 1.0, v168
	v_add_f32_e32 v169, 1.0, v169
	v_exp_f32_e32 v170, v170
	v_exp_f32_e32 v171, v171
	v_exp_f32_e32 v172, v172
	v_exp_f32_e32 v173, v173
	v_rcp_f32_e32 v164, v164
	v_rcp_f32_e32 v165, v165
	v_rcp_f32_e32 v168, v168
	v_rcp_f32_e32 v169, v169
	v_add_f32_e32 v170, 1.0, v170
	v_add_f32_e32 v171, 1.0, v171
	v_add_f32_e32 v172, 1.0, v172
	v_add_f32_e32 v173, 1.0, v173
	v_pk_mul_f32 v[164:165], v[8:9], v[164:165]
	v_pk_mul_f32 v[168:169], v[10:11], v[168:169]
	v_rcp_f32_e32 v170, v170
	v_rcp_f32_e32 v171, v171
	v_rcp_f32_e32 v172, v172
	v_rcp_f32_e32 v173, v173
	v_pk_mul_f32 v[164:165], v[164:165], v[72:73]
	v_pk_mul_f32 v[168:169], v[168:169], v[74:75]
	v_cvt_pk_bf16_f32 v164, v164, v165
	v_cvt_pk_bf16_f32 v165, v168, v169
	v_mul_f32_e32 v168, 0xbfb8aa3b, v0
	v_mul_f32_e32 v169, 0xbfb8aa3b, v1
	v_exp_f32_e32 v168, v168
	v_exp_f32_e32 v169, v169
	v_mad_u64_u32 v[166:167], s[18:19], s78, v160, 0
	v_pk_mul_f32 v[170:171], v[12:13], v[170:171]
; DI unsigned pk2(float lo, float hi) { f32x2 v = {lo, hi}; bf16v2 b = __builtin_convertvector(v, bf16v2); return __builtin_bit_cast(unsigned, b); }
; DI float silu_f(float x) { return x * __builtin_amdgcn_rcpf(1.f + __expf(-x)); }
;     DI void operator()(const f32x4 (&acc)[2][2][4][2], const Unit& u, int wr, int wc, int fr, int fq) const {
;     ...
;             for (int m = 0; m < 4; ++m) { bf16_t* rowp = O + (size_t)(row0 + ai * HALF + m * 16) * ldc + col0;
;                 float r[8];
; #pragma unroll
;                 for (int n = 0; n < 2; ++n)
; #pragma unroll
;                     for (int e = 0; e < 4; ++e) { const float g = acc[ai][0][m][n][e], up = acc[ai][1][m][n][e]; r[n * 4 + e] = silu_f(g) * up; }
;                 u32x4 o; o.x = pk2(r[0], r[1]); o.y = pk2(r[2], r[3]); o.z = pk2(r[4], r[5]); o.w = pk2(r[6], r[7]);
;                 *(u32x4*)rowp = o; }
	v_pk_mul_f32 v[172:173], v[14:15], v[172:173]
	v_add3_u32 v167, v167, v157, v161
	v_pk_mul_f32 v[170:171], v[170:171], v[76:77]
	v_pk_mul_f32 v[172:173], v[172:173], v[78:79]
	v_lshl_add_u64 v[174:175], v[166:167], 1, v[140:141]
	v_cvt_pk_bf16_f32 v166, v170, v171
	v_cvt_pk_bf16_f32 v167, v172, v173
	global_store_dwordx4 v[174:175], v[164:167], off
	v_mul_f32_e32 v170, 0xbfb8aa3b, v4
	v_mul_f32_e32 v171, 0xbfb8aa3b, v5
	v_add_f32_e32 v164, 1.0, v168
	v_add_f32_e32 v165, 1.0, v169
	v_mul_f32_e32 v168, 0xbfb8aa3b, v2
	v_mul_f32_e32 v169, 0xbfb8aa3b, v3
	v_mul_f32_e32 v172, 0xbfb8aa3b, v6
	v_mul_f32_e32 v173, 0xbfb8aa3b, v7
	v_exp_f32_e32 v168, v168
	v_exp_f32_e32 v169, v169
	v_exp_f32_e32 v170, v170
	v_exp_f32_e32 v171, v171
	v_exp_f32_e32 v172, v172
	v_exp_f32_e32 v173, v173
	v_add_f32_e32 v168, 1.0, v168
	v_add_f32_e32 v169, 1.0, v169
	v_add_f32_e32 v170, 1.0, v170
	v_add_f32_e32 v171, 1.0, v171
	v_add_f32_e32 v172, 1.0, v172
	v_add_f32_e32 v173, 1.0, v173
	v_rcp_f32_e32 v164, v164
	v_rcp_f32_e32 v165, v165
	v_rcp_f32_e32 v168, v168
	v_rcp_f32_e32 v169, v169
	v_rcp_f32_e32 v170, v170
	v_rcp_f32_e32 v171, v171
	v_rcp_f32_e32 v172, v172
	v_rcp_f32_e32 v173, v173
	v_mad_u64_u32 v[166:167], s[18:19], s78, v158, 0
	v_pk_mul_f32 v[164:165], v[0:1], v[164:165]
	v_pk_mul_f32 v[168:169], v[2:3], v[168:169]
	v_pk_mul_f32 v[170:171], v[4:5], v[170:171]
	v_pk_mul_f32 v[172:173], v[6:7], v[172:173]
	v_add3_u32 v167, v167, v157, v159
	v_pk_mul_f32 v[164:165], v[164:165], v[56:57]
	v_pk_mul_f32 v[168:169], v[168:169], v[58:59]
	v_pk_mul_f32 v[170:171], v[170:171], v[64:65]
	v_pk_mul_f32 v[172:173], v[172:173], v[66:67]
	v_lshl_add_u64 v[174:175], v[166:167], 1, v[140:141]
	v_cvt_pk_bf16_f32 v164, v164, v165
	v_cvt_pk_bf16_f32 v165, v168, v169
	v_cvt_pk_bf16_f32 v166, v170, v171
	v_cvt_pk_bf16_f32 v167, v172, v173
	global_store_dwordx4 v[174:175], v[164:167], off
	v_mul_lo_u32 v168, s78, v156
	v_mul_f32_e32 v169, 0xbfb8aa3b, v63
	v_mad_u64_u32 v[166:167], s[18:19], s78, v154, 0
	v_mul_f32_e32 v164, 0xbfb8aa3b, v60
	v_mul_f32_e32 v165, 0xbfb8aa3b, v61
	v_add3_u32 v167, v167, v168, v155
	v_mul_f32_e32 v168, 0xbfb8aa3b, v62
	v_mul_f32_e32 v170, 0xbfb8aa3b, v68
	v_mul_f32_e32 v171, 0xbfb8aa3b, v69
	v_mul_f32_e32 v172, 0xbfb8aa3b, v70
	v_mul_f32_e32 v173, 0xbfb8aa3b, v71
	v_exp_f32_e32 v164, v164
	v_exp_f32_e32 v165, v165
	v_exp_f32_e32 v168, v168
	v_exp_f32_e32 v169, v169
	v_exp_f32_e32 v170, v170
	v_exp_f32_e32 v171, v171
	v_exp_f32_e32 v172, v172
	v_exp_f32_e32 v173, v173
	v_add_f32_e32 v164, 1.0, v164
	v_add_f32_e32 v165, 1.0, v165
	v_add_f32_e32 v168, 1.0, v168
	v_add_f32_e32 v169, 1.0, v169
	v_add_f32_e32 v170, 1.0, v170
	v_add_f32_e32 v171, 1.0, v171
	v_add_f32_e32 v172, 1.0, v172
	v_add_f32_e32 v173, 1.0, v173
	v_rcp_f32_e32 v164, v164
	v_rcp_f32_e32 v165, v165
	v_rcp_f32_e32 v168, v168
	v_rcp_f32_e32 v169, v169
	v_rcp_f32_e32 v170, v170
	v_rcp_f32_e32 v171, v171
	v_rcp_f32_e32 v172, v172
	v_rcp_f32_e32 v173, v173
	v_pk_mul_f32 v[164:165], v[60:61], v[164:165]
	v_pk_mul_f32 v[168:169], v[62:63], v[168:169]
	v_pk_mul_f32 v[170:171], v[68:69], v[170:171]
	v_pk_mul_f32 v[172:173], v[70:71], v[172:173]
	v_pk_mul_f32 v[164:165], v[164:165], v[120:121]
	v_pk_mul_f32 v[168:169], v[168:169], v[122:123]
	v_pk_mul_f32 v[170:171], v[170:171], v[124:125]
	v_pk_mul_f32 v[172:173], v[172:173], v[126:127]
	v_lshl_add_u64 v[174:175], v[166:167], 1, v[140:141]
	v_cvt_pk_bf16_f32 v164, v164, v165
	v_cvt_pk_bf16_f32 v165, v168, v169
	v_cvt_pk_bf16_f32 v166, v170, v171
	v_cvt_pk_bf16_f32 v167, v172, v173
	global_store_dwordx4 v[174:175], v[164:167], off
	v_mul_lo_u32 v168, s78, v153
	v_mul_f32_e32 v169, 0xbfb8aa3b, v51
	v_mad_u64_u32 v[166:167], s[18:19], s78, v151, 0
	v_mul_f32_e32 v164, 0xbfb8aa3b, v48
	v_mul_f32_e32 v165, 0xbfb8aa3b, v49
	v_add3_u32 v167, v167, v168, v152
	v_mul_f32_e32 v168, 0xbfb8aa3b, v50
	v_mul_f32_e32 v170, 0xbfb8aa3b, v52
	v_mul_f32_e32 v171, 0xbfb8aa3b, v53
	v_mul_f32_e32 v172, 0xbfb8aa3b, v54
	v_mul_f32_e32 v173, 0xbfb8aa3b, v55
	v_exp_f32_e32 v164, v164
	v_exp_f32_e32 v165, v165
	v_exp_f32_e32 v168, v168
	v_exp_f32_e32 v169, v169
	v_exp_f32_e32 v170, v170
	v_exp_f32_e32 v171, v171
	v_exp_f32_e32 v172, v172
	v_exp_f32_e32 v173, v173
	v_add_f32_e32 v164, 1.0, v164
	v_add_f32_e32 v165, 1.0, v165
	v_add_f32_e32 v168, 1.0, v168
	v_add_f32_e32 v169, 1.0, v169
	v_add_f32_e32 v170, 1.0, v170
	v_add_f32_e32 v171, 1.0, v171
	v_add_f32_e32 v172, 1.0, v172
	v_add_f32_e32 v173, 1.0, v173
; DI unsigned pk2(float lo, float hi) { f32x2 v = {lo, hi}; bf16v2 b = __builtin_convertvector(v, bf16v2); return __builtin_bit_cast(unsigned, b); }
; DI float silu_f(float x) { return x * __builtin_amdgcn_rcpf(1.f + __expf(-x)); }
;     DI void operator()(const f32x4 (&acc)[2][2][4][2], const Unit& u, int wr, int wc, int fr, int fq) const {
;     ...
;             for (int m = 0; m < 4; ++m) { bf16_t* rowp = O + (size_t)(row0 + ai * HALF + m * 16) * ldc + col0;
;                 float r[8];
; #pragma unroll
;                 for (int n = 0; n < 2; ++n)
; #pragma unroll
;                     for (int e = 0; e < 4; ++e) { const float g = acc[ai][0][m][n][e], up = acc[ai][1][m][n][e]; r[n * 4 + e] = silu_f(g) * up; }
;                 u32x4 o; o.x = pk2(r[0], r[1]); o.y = pk2(r[2], r[3]); o.z = pk2(r[4], r[5]); o.w = pk2(r[6], r[7]);
;                 *(u32x4*)rowp = o; }
	v_rcp_f32_e32 v164, v164
	v_rcp_f32_e32 v165, v165
	v_rcp_f32_e32 v168, v168
	v_rcp_f32_e32 v169, v169
	v_rcp_f32_e32 v170, v170
	v_rcp_f32_e32 v171, v171
	v_rcp_f32_e32 v172, v172
	v_rcp_f32_e32 v173, v173
	v_pk_mul_f32 v[164:165], v[48:49], v[164:165]
	v_pk_mul_f32 v[168:169], v[50:51], v[168:169]
	v_pk_mul_f32 v[170:171], v[52:53], v[170:171]
	v_pk_mul_f32 v[172:173], v[54:55], v[172:173]
	v_pk_mul_f32 v[164:165], v[164:165], v[112:113]
	v_pk_mul_f32 v[168:169], v[168:169], v[114:115]
	v_pk_mul_f32 v[170:171], v[170:171], v[116:117]
	v_pk_mul_f32 v[172:173], v[172:173], v[118:119]
	v_lshl_add_u64 v[174:175], v[166:167], 1, v[140:141]
	v_cvt_pk_bf16_f32 v164, v164, v165
	v_cvt_pk_bf16_f32 v165, v168, v169
	v_cvt_pk_bf16_f32 v166, v170, v171
	v_cvt_pk_bf16_f32 v167, v172, v173
	global_store_dwordx4 v[174:175], v[164:167], off
	v_mul_lo_u32 v169, s79, v150
	v_mul_f32_e32 v170, 0xbfb8aa3b, v44
	v_ashrrev_i32_e32 v164, 31, v150
	v_mul_lo_u32 v168, s78, v164
	v_mad_u64_u32 v[166:167], s[18:19], s78, v150, 0
	v_mul_f32_e32 v164, 0xbfb8aa3b, v40
	v_mul_f32_e32 v165, 0xbfb8aa3b, v41
	v_add3_u32 v167, v167, v168, v169
	v_mul_f32_e32 v168, 0xbfb8aa3b, v42
	v_mul_f32_e32 v169, 0xbfb8aa3b, v43
	v_mul_f32_e32 v171, 0xbfb8aa3b, v45
	v_mul_f32_e32 v172, 0xbfb8aa3b, v46
	v_mul_f32_e32 v173, 0xbfb8aa3b, v47
	v_exp_f32_e32 v164, v164
	v_exp_f32_e32 v165, v165
	v_exp_f32_e32 v168, v168
	v_exp_f32_e32 v169, v169
	v_exp_f32_e32 v170, v170
	v_exp_f32_e32 v171, v171
	v_exp_f32_e32 v172, v172
	v_exp_f32_e32 v173, v173
	v_add_f32_e32 v164, 1.0, v164
	v_add_f32_e32 v165, 1.0, v165
	v_add_f32_e32 v168, 1.0, v168
	v_add_f32_e32 v169, 1.0, v169
	v_add_f32_e32 v170, 1.0, v170
	v_add_f32_e32 v171, 1.0, v171
	v_add_f32_e32 v172, 1.0, v172
	v_add_f32_e32 v173, 1.0, v173
	v_rcp_f32_e32 v164, v164
	v_rcp_f32_e32 v165, v165
	v_rcp_f32_e32 v168, v168
	v_rcp_f32_e32 v169, v169
	v_rcp_f32_e32 v170, v170
	v_rcp_f32_e32 v171, v171
	v_rcp_f32_e32 v172, v172
	v_rcp_f32_e32 v173, v173
	v_pk_mul_f32 v[164:165], v[40:41], v[164:165]
	v_pk_mul_f32 v[168:169], v[42:43], v[168:169]
	v_pk_mul_f32 v[170:171], v[44:45], v[170:171]
	v_pk_mul_f32 v[172:173], v[46:47], v[172:173]
	v_pk_mul_f32 v[164:165], v[164:165], v[104:105]
	v_pk_mul_f32 v[168:169], v[168:169], v[106:107]
	v_pk_mul_f32 v[170:171], v[170:171], v[108:109]
	v_pk_mul_f32 v[172:173], v[172:173], v[110:111]
	v_lshl_add_u64 v[174:175], v[166:167], 1, v[140:141]
	v_cvt_pk_bf16_f32 v164, v164, v165
	v_cvt_pk_bf16_f32 v165, v168, v169
	v_cvt_pk_bf16_f32 v166, v170, v171
	v_cvt_pk_bf16_f32 v167, v172, v173
	global_store_dwordx4 v[174:175], v[164:167], off
	v_mul_lo_u32 v169, s79, v149
	v_mul_f32_e32 v170, 0xbfb8aa3b, v36
	v_ashrrev_i32_e32 v164, 31, v149
	v_mul_lo_u32 v168, s78, v164
	v_mad_u64_u32 v[166:167], s[18:19], s78, v149, 0
	v_mul_f32_e32 v164, 0xbfb8aa3b, v32
	v_mul_f32_e32 v165, 0xbfb8aa3b, v33
	v_add3_u32 v167, v167, v168, v169
	v_mul_f32_e32 v168, 0xbfb8aa3b, v34
	v_mul_f32_e32 v169, 0xbfb8aa3b, v35
	v_mul_f32_e32 v171, 0xbfb8aa3b, v37
	v_mul_f32_e32 v172, 0xbfb8aa3b, v38
	v_mul_f32_e32 v173, 0xbfb8aa3b, v39
	v_exp_f32_e32 v164, v164
	v_exp_f32_e32 v165, v165
	v_exp_f32_e32 v168, v168
	v_exp_f32_e32 v169, v169
	v_exp_f32_e32 v170, v170
	v_exp_f32_e32 v171, v171
	v_exp_f32_e32 v172, v172
	v_exp_f32_e32 v173, v173
	v_add_f32_e32 v164, 1.0, v164
	v_add_f32_e32 v165, 1.0, v165
	v_add_f32_e32 v168, 1.0, v168
	v_add_f32_e32 v169, 1.0, v169
	v_add_f32_e32 v170, 1.0, v170
	v_add_f32_e32 v171, 1.0, v171
	v_add_f32_e32 v172, 1.0, v172
	v_add_f32_e32 v173, 1.0, v173
	v_rcp_f32_e32 v164, v164
	v_rcp_f32_e32 v165, v165
	v_rcp_f32_e32 v168, v168
	v_rcp_f32_e32 v169, v169
	v_rcp_f32_e32 v170, v170
	v_rcp_f32_e32 v171, v171
	v_rcp_f32_e32 v172, v172
	v_rcp_f32_e32 v173, v173
	v_pk_mul_f32 v[164:165], v[32:33], v[164:165]
	v_pk_mul_f32 v[168:169], v[34:35], v[168:169]
	v_pk_mul_f32 v[170:171], v[36:37], v[170:171]
	v_pk_mul_f32 v[172:173], v[38:39], v[172:173]
	v_pk_mul_f32 v[164:165], v[164:165], v[92:93]
	v_pk_mul_f32 v[168:169], v[168:169], v[94:95]
	v_pk_mul_f32 v[170:171], v[170:171], v[100:101]
	v_pk_mul_f32 v[172:173], v[172:173], v[102:103]
	v_lshl_add_u64 v[140:141], v[166:167], 1, v[140:141]
	v_cvt_pk_bf16_f32 v164, v164, v165
	v_cvt_pk_bf16_f32 v165, v168, v169
	v_cvt_pk_bf16_f32 v166, v170, v171
	v_cvt_pk_bf16_f32 v167, v172, v173
	global_store_dwordx4 v[140:141], v[164:167], off
	s_cbranch_execnz .LBB0_748
	s_branch .LBB0_747

; DI f32x4 zero4() { float a, b, c, d; asm volatile("v_mov_b32 %0, 0\n\tv_mov_b32 %1, 0\n\tv_mov_b32 %2, 0\n\tv_mov_b32 %3, 0\n\ts_nop 1" : "=v"(a), "=v"(b), "=v"(c), "=v"(d)); return (f32x4){a, b, c, d}; }
; template <class Epi>
; DI void gemm_phase(LAS unsigned char* lds, const Gemm g, const StaticOrder& S, const Epi& E, const int tid) {
;     ...
;         if (!has_next) break;
; #pragma unroll
;         for (int a = 0; a < 2; ++a)
; #pragma unroll
;             for (int b = 0; b < 2; ++b)
; #pragma unroll
;                 for (int m = 0; m < 4; ++m)
; #pragma unroll
;                     for (int n = 0; n < 2; ++n) acc[a][b][m][n] = zero4();
;         cur = nxt; cA = nA; cB = nB; ++ui;
.LBB0_748:
	s_and_b64 vcc, exec, s[6:7]
	s_mov_b64 s[6:7], -1
	s_cbranch_vccnz .LBB0_735
	s_mov_b64 s[6:7], 0
	s_branch .LBB0_735
